# final norm: split-K slab fold loops process the parts four loads at a time, same accumulation order (was one load round trip per part, 40 per tail row)
# speedup vs baseline: 1.0079x; 1.0079x over previous
.LBB0_2210:
.Lmy_ff0_g:
	global_load_dwordx4 v[34:37], v[32:33], off
	v_lshl_add_u64 v[32:33], v[32:33], 0, s[4:5]
	s_cmp_lt_u32 s2, 2
	s_cbranch_scc1 .Lmy_ff0_w1
	global_load_dwordx4 v[140:143], v[32:33], off
	v_lshl_add_u64 v[32:33], v[32:33], 0, s[4:5]
	s_cmp_lt_u32 s2, 3
	s_cbranch_scc1 .Lmy_ff0_w2
	global_load_dwordx4 v[144:147], v[32:33], off
	v_lshl_add_u64 v[32:33], v[32:33], 0, s[4:5]
	s_cmp_lt_u32 s2, 4
	s_cbranch_scc1 .Lmy_ff0_w3
	global_load_dwordx4 v[148:151], v[32:33], off
	v_lshl_add_u64 v[32:33], v[32:33], 0, s[4:5]
	s_waitcnt vmcnt(0)
	v_lshlrev_b32_e32 v38, 16, v34
	v_and_b32_e32 v39, 0xffff0000, v34
	v_lshlrev_b32_e32 v34, 16, v35
	v_and_b32_e32 v35, 0xffff0000, v35
	v_lshlrev_b32_e32 v40, 16, v36
	v_and_b32_e32 v41, 0xffff0000, v36
	v_lshlrev_b32_e32 v36, 16, v37
	v_and_b32_e32 v37, 0xffff0000, v37
	v_pk_add_f32 v[24:25], v[24:25], v[38:39]
	v_pk_add_f32 v[26:27], v[26:27], v[34:35]
	v_pk_add_f32 v[28:29], v[28:29], v[40:41]
	v_pk_add_f32 v[30:31], v[30:31], v[36:37]
	v_lshlrev_b32_e32 v38, 16, v140
	v_and_b32_e32 v39, 0xffff0000, v140
	v_lshlrev_b32_e32 v140, 16, v141
	v_and_b32_e32 v141, 0xffff0000, v141
	v_lshlrev_b32_e32 v40, 16, v142
	v_and_b32_e32 v41, 0xffff0000, v142
	v_lshlrev_b32_e32 v142, 16, v143
	v_and_b32_e32 v143, 0xffff0000, v143
	v_pk_add_f32 v[24:25], v[24:25], v[38:39]
	v_pk_add_f32 v[26:27], v[26:27], v[140:141]
	v_pk_add_f32 v[28:29], v[28:29], v[40:41]
	v_pk_add_f32 v[30:31], v[30:31], v[142:143]
	v_lshlrev_b32_e32 v38, 16, v144
	v_and_b32_e32 v39, 0xffff0000, v144
	v_lshlrev_b32_e32 v144, 16, v145
	v_and_b32_e32 v145, 0xffff0000, v145
	v_lshlrev_b32_e32 v40, 16, v146
	v_and_b32_e32 v41, 0xffff0000, v146
	v_lshlrev_b32_e32 v146, 16, v147
	v_and_b32_e32 v147, 0xffff0000, v147
	v_pk_add_f32 v[24:25], v[24:25], v[38:39]
	v_pk_add_f32 v[26:27], v[26:27], v[144:145]
	v_pk_add_f32 v[28:29], v[28:29], v[40:41]
	v_pk_add_f32 v[30:31], v[30:31], v[146:147]
	v_lshlrev_b32_e32 v38, 16, v148
	v_and_b32_e32 v39, 0xffff0000, v148
	v_lshlrev_b32_e32 v148, 16, v149
	v_and_b32_e32 v149, 0xffff0000, v149
	v_lshlrev_b32_e32 v40, 16, v150
	v_and_b32_e32 v41, 0xffff0000, v150
	v_lshlrev_b32_e32 v150, 16, v151
	v_and_b32_e32 v151, 0xffff0000, v151
	v_pk_add_f32 v[24:25], v[24:25], v[38:39]
	v_pk_add_f32 v[26:27], v[26:27], v[148:149]
	v_pk_add_f32 v[28:29], v[28:29], v[40:41]
	v_pk_add_f32 v[30:31], v[30:31], v[150:151]
	s_sub_u32 s2, s2, 4
	s_cmp_eq_u32 s2, 0
	s_cbranch_scc0 .Lmy_ff0_g
	s_branch .Lmy_ff0_d
.Lmy_ff0_w3:
	s_waitcnt vmcnt(0)
	v_lshlrev_b32_e32 v38, 16, v34
	v_and_b32_e32 v39, 0xffff0000, v34
	v_lshlrev_b32_e32 v34, 16, v35
	v_and_b32_e32 v35, 0xffff0000, v35
	v_lshlrev_b32_e32 v40, 16, v36
	v_and_b32_e32 v41, 0xffff0000, v36
	v_lshlrev_b32_e32 v36, 16, v37
	v_and_b32_e32 v37, 0xffff0000, v37
	v_pk_add_f32 v[24:25], v[24:25], v[38:39]
	v_pk_add_f32 v[26:27], v[26:27], v[34:35]
	v_pk_add_f32 v[28:29], v[28:29], v[40:41]
	v_pk_add_f32 v[30:31], v[30:31], v[36:37]
	v_lshlrev_b32_e32 v38, 16, v140
	v_and_b32_e32 v39, 0xffff0000, v140
	v_lshlrev_b32_e32 v140, 16, v141
	v_and_b32_e32 v141, 0xffff0000, v141
	v_lshlrev_b32_e32 v40, 16, v142
	v_and_b32_e32 v41, 0xffff0000, v142
	v_lshlrev_b32_e32 v142, 16, v143
	v_and_b32_e32 v143, 0xffff0000, v143
	v_pk_add_f32 v[24:25], v[24:25], v[38:39]
	v_pk_add_f32 v[26:27], v[26:27], v[140:141]
	v_pk_add_f32 v[28:29], v[28:29], v[40:41]
	v_pk_add_f32 v[30:31], v[30:31], v[142:143]
	v_lshlrev_b32_e32 v38, 16, v144
	v_and_b32_e32 v39, 0xffff0000, v144
	v_lshlrev_b32_e32 v144, 16, v145
	v_and_b32_e32 v145, 0xffff0000, v145
	v_lshlrev_b32_e32 v40, 16, v146
	v_and_b32_e32 v41, 0xffff0000, v146
	v_lshlrev_b32_e32 v146, 16, v147
	v_and_b32_e32 v147, 0xffff0000, v147
	v_pk_add_f32 v[24:25], v[24:25], v[38:39]
	v_pk_add_f32 v[26:27], v[26:27], v[144:145]
	v_pk_add_f32 v[28:29], v[28:29], v[40:41]
	v_pk_add_f32 v[30:31], v[30:31], v[146:147]
	s_branch .Lmy_ff0_d
.Lmy_ff0_w2:
	s_waitcnt vmcnt(0)
	v_lshlrev_b32_e32 v38, 16, v34
	v_and_b32_e32 v39, 0xffff0000, v34
	v_lshlrev_b32_e32 v34, 16, v35
	v_and_b32_e32 v35, 0xffff0000, v35
	v_lshlrev_b32_e32 v40, 16, v36
	v_and_b32_e32 v41, 0xffff0000, v36
	v_lshlrev_b32_e32 v36, 16, v37
	v_and_b32_e32 v37, 0xffff0000, v37
	v_pk_add_f32 v[24:25], v[24:25], v[38:39]
	v_pk_add_f32 v[26:27], v[26:27], v[34:35]
	v_pk_add_f32 v[28:29], v[28:29], v[40:41]
	v_pk_add_f32 v[30:31], v[30:31], v[36:37]
	v_lshlrev_b32_e32 v38, 16, v140
	v_and_b32_e32 v39, 0xffff0000, v140
	v_lshlrev_b32_e32 v140, 16, v141
	v_and_b32_e32 v141, 0xffff0000, v141
	v_lshlrev_b32_e32 v40, 16, v142
	v_and_b32_e32 v41, 0xffff0000, v142
	v_lshlrev_b32_e32 v142, 16, v143
	v_and_b32_e32 v143, 0xffff0000, v143
	v_pk_add_f32 v[24:25], v[24:25], v[38:39]
	v_pk_add_f32 v[26:27], v[26:27], v[140:141]
	v_pk_add_f32 v[28:29], v[28:29], v[40:41]
	v_pk_add_f32 v[30:31], v[30:31], v[142:143]
	s_branch .Lmy_ff0_d
.Lmy_ff0_w1:
	s_waitcnt vmcnt(0)
	v_lshlrev_b32_e32 v38, 16, v34
	v_and_b32_e32 v39, 0xffff0000, v34
	v_lshlrev_b32_e32 v34, 16, v35
	v_and_b32_e32 v35, 0xffff0000, v35
	v_lshlrev_b32_e32 v40, 16, v36
	v_and_b32_e32 v41, 0xffff0000, v36
	v_lshlrev_b32_e32 v36, 16, v37
	v_and_b32_e32 v37, 0xffff0000, v37
	v_pk_add_f32 v[24:25], v[24:25], v[38:39]
	v_pk_add_f32 v[26:27], v[26:27], v[34:35]
	v_pk_add_f32 v[28:29], v[28:29], v[40:41]
	v_pk_add_f32 v[30:31], v[30:31], v[36:37]
.Lmy_ff0_d:
	v_cvt_pk_bf16_f32 v12, v24, v25
	v_cvt_pk_bf16_f32 v27, v26, v27
	v_cvt_pk_bf16_f32 v29, v28, v29
	v_cvt_pk_bf16_f32 v31, v30, v31
	v_lshlrev_b32_e32 v24, 16, v12
	v_and_b32_e32 v25, 0xffff0000, v12
	v_lshlrev_b32_e32 v26, 16, v27
	v_and_b32_e32 v27, 0xffff0000, v27
	v_lshlrev_b32_e32 v28, 16, v29
	v_and_b32_e32 v29, 0xffff0000, v29
	v_lshlrev_b32_e32 v30, 16, v31
	v_and_b32_e32 v31, 0xffff0000, v31

.LBB0_2214:
.Lmy_ff1_g:
	global_load_dwordx4 v[38:41], v[36:37], off
	v_lshl_add_u64 v[36:37], v[36:37], 0, s[4:5]
	s_cmp_lt_u32 s2, 2
	s_cbranch_scc1 .Lmy_ff1_w1
	global_load_dwordx4 v[140:143], v[36:37], off
	v_lshl_add_u64 v[36:37], v[36:37], 0, s[4:5]
	s_cmp_lt_u32 s2, 3
	s_cbranch_scc1 .Lmy_ff1_w2
	global_load_dwordx4 v[144:147], v[36:37], off
	v_lshl_add_u64 v[36:37], v[36:37], 0, s[4:5]
	s_cmp_lt_u32 s2, 4
	s_cbranch_scc1 .Lmy_ff1_w3
	global_load_dwordx4 v[148:151], v[36:37], off
	v_lshl_add_u64 v[36:37], v[36:37], 0, s[4:5]
	s_waitcnt vmcnt(0)
	v_lshlrev_b32_e32 v44, 16, v38
	v_and_b32_e32 v45, 0xffff0000, v38
	v_lshlrev_b32_e32 v38, 16, v39
	v_and_b32_e32 v39, 0xffff0000, v39
	v_lshlrev_b32_e32 v52, 16, v40
	v_and_b32_e32 v53, 0xffff0000, v40
	v_lshlrev_b32_e32 v40, 16, v41
	v_and_b32_e32 v41, 0xffff0000, v41
	v_pk_add_f32 v[32:33], v[32:33], v[44:45]
	v_pk_add_f32 v[8:9], v[8:9], v[38:39]
	v_pk_add_f32 v[34:35], v[34:35], v[52:53]
	v_pk_add_f32 v[10:11], v[10:11], v[40:41]
	v_lshlrev_b32_e32 v44, 16, v140
	v_and_b32_e32 v45, 0xffff0000, v140
	v_lshlrev_b32_e32 v140, 16, v141
	v_and_b32_e32 v141, 0xffff0000, v141
	v_lshlrev_b32_e32 v52, 16, v142
	v_and_b32_e32 v53, 0xffff0000, v142
	v_lshlrev_b32_e32 v142, 16, v143
	v_and_b32_e32 v143, 0xffff0000, v143
	v_pk_add_f32 v[32:33], v[32:33], v[44:45]
	v_pk_add_f32 v[8:9], v[8:9], v[140:141]
	v_pk_add_f32 v[34:35], v[34:35], v[52:53]
	v_pk_add_f32 v[10:11], v[10:11], v[142:143]
	v_lshlrev_b32_e32 v44, 16, v144
	v_and_b32_e32 v45, 0xffff0000, v144
	v_lshlrev_b32_e32 v144, 16, v145
	v_and_b32_e32 v145, 0xffff0000, v145
	v_lshlrev_b32_e32 v52, 16, v146
	v_and_b32_e32 v53, 0xffff0000, v146
	v_lshlrev_b32_e32 v146, 16, v147
	v_and_b32_e32 v147, 0xffff0000, v147
	v_pk_add_f32 v[32:33], v[32:33], v[44:45]
	v_pk_add_f32 v[8:9], v[8:9], v[144:145]
	v_pk_add_f32 v[34:35], v[34:35], v[52:53]
	v_pk_add_f32 v[10:11], v[10:11], v[146:147]
	v_lshlrev_b32_e32 v44, 16, v148
	v_and_b32_e32 v45, 0xffff0000, v148
	v_lshlrev_b32_e32 v148, 16, v149
	v_and_b32_e32 v149, 0xffff0000, v149
	v_lshlrev_b32_e32 v52, 16, v150
	v_and_b32_e32 v53, 0xffff0000, v150
	v_lshlrev_b32_e32 v150, 16, v151
	v_and_b32_e32 v151, 0xffff0000, v151
	v_pk_add_f32 v[32:33], v[32:33], v[44:45]
	v_pk_add_f32 v[8:9], v[8:9], v[148:149]
	v_pk_add_f32 v[34:35], v[34:35], v[52:53]
	v_pk_add_f32 v[10:11], v[10:11], v[150:151]
	s_sub_u32 s2, s2, 4
	s_cmp_eq_u32 s2, 0
	s_cbranch_scc0 .Lmy_ff1_g
	s_branch .Lmy_ff1_d
.Lmy_ff1_w3:
	s_waitcnt vmcnt(0)
	v_lshlrev_b32_e32 v44, 16, v38
	v_and_b32_e32 v45, 0xffff0000, v38
	v_lshlrev_b32_e32 v38, 16, v39
	v_and_b32_e32 v39, 0xffff0000, v39
	v_lshlrev_b32_e32 v52, 16, v40
	v_and_b32_e32 v53, 0xffff0000, v40
	v_lshlrev_b32_e32 v40, 16, v41
	v_and_b32_e32 v41, 0xffff0000, v41
	v_pk_add_f32 v[32:33], v[32:33], v[44:45]
	v_pk_add_f32 v[8:9], v[8:9], v[38:39]
	v_pk_add_f32 v[34:35], v[34:35], v[52:53]
	v_pk_add_f32 v[10:11], v[10:11], v[40:41]
	v_lshlrev_b32_e32 v44, 16, v140
	v_and_b32_e32 v45, 0xffff0000, v140
	v_lshlrev_b32_e32 v140, 16, v141
	v_and_b32_e32 v141, 0xffff0000, v141
	v_lshlrev_b32_e32 v52, 16, v142
	v_and_b32_e32 v53, 0xffff0000, v142
	v_lshlrev_b32_e32 v142, 16, v143
	v_and_b32_e32 v143, 0xffff0000, v143
	v_pk_add_f32 v[32:33], v[32:33], v[44:45]
	v_pk_add_f32 v[8:9], v[8:9], v[140:141]
	v_pk_add_f32 v[34:35], v[34:35], v[52:53]
	v_pk_add_f32 v[10:11], v[10:11], v[142:143]
	v_lshlrev_b32_e32 v44, 16, v144
	v_and_b32_e32 v45, 0xffff0000, v144
	v_lshlrev_b32_e32 v144, 16, v145
	v_and_b32_e32 v145, 0xffff0000, v145
	v_lshlrev_b32_e32 v52, 16, v146
	v_and_b32_e32 v53, 0xffff0000, v146
	v_lshlrev_b32_e32 v146, 16, v147
	v_and_b32_e32 v147, 0xffff0000, v147
	v_pk_add_f32 v[32:33], v[32:33], v[44:45]
	v_pk_add_f32 v[8:9], v[8:9], v[144:145]
	v_pk_add_f32 v[34:35], v[34:35], v[52:53]
	v_pk_add_f32 v[10:11], v[10:11], v[146:147]
	s_branch .Lmy_ff1_d
.Lmy_ff1_w2:
	s_waitcnt vmcnt(0)
	v_lshlrev_b32_e32 v44, 16, v38
	v_and_b32_e32 v45, 0xffff0000, v38
	v_lshlrev_b32_e32 v38, 16, v39
	v_and_b32_e32 v39, 0xffff0000, v39
	v_lshlrev_b32_e32 v52, 16, v40
	v_and_b32_e32 v53, 0xffff0000, v40
	v_lshlrev_b32_e32 v40, 16, v41
	v_and_b32_e32 v41, 0xffff0000, v41
	v_pk_add_f32 v[32:33], v[32:33], v[44:45]
	v_pk_add_f32 v[8:9], v[8:9], v[38:39]
	v_pk_add_f32 v[34:35], v[34:35], v[52:53]
	v_pk_add_f32 v[10:11], v[10:11], v[40:41]
	v_lshlrev_b32_e32 v44, 16, v140
	v_and_b32_e32 v45, 0xffff0000, v140
	v_lshlrev_b32_e32 v140, 16, v141
	v_and_b32_e32 v141, 0xffff0000, v141
	v_lshlrev_b32_e32 v52, 16, v142
	v_and_b32_e32 v53, 0xffff0000, v142
	v_lshlrev_b32_e32 v142, 16, v143
	v_and_b32_e32 v143, 0xffff0000, v143
	v_pk_add_f32 v[32:33], v[32:33], v[44:45]
	v_pk_add_f32 v[8:9], v[8:9], v[140:141]
	v_pk_add_f32 v[34:35], v[34:35], v[52:53]
	v_pk_add_f32 v[10:11], v[10:11], v[142:143]
	s_branch .Lmy_ff1_d
.Lmy_ff1_w1:
	s_waitcnt vmcnt(0)
	v_lshlrev_b32_e32 v44, 16, v38
	v_and_b32_e32 v45, 0xffff0000, v38
	v_lshlrev_b32_e32 v38, 16, v39
	v_and_b32_e32 v39, 0xffff0000, v39
	v_lshlrev_b32_e32 v52, 16, v40
	v_and_b32_e32 v53, 0xffff0000, v40
	v_lshlrev_b32_e32 v40, 16, v41
	v_and_b32_e32 v41, 0xffff0000, v41
	v_pk_add_f32 v[32:33], v[32:33], v[44:45]
	v_pk_add_f32 v[8:9], v[8:9], v[38:39]
	v_pk_add_f32 v[34:35], v[34:35], v[52:53]
	v_pk_add_f32 v[10:11], v[10:11], v[40:41]
.Lmy_ff1_d:
	v_cvt_pk_bf16_f32 v12, v32, v33
	v_cvt_pk_bf16_f32 v9, v8, v9
	v_cvt_pk_bf16_f32 v35, v34, v35
	v_cvt_pk_bf16_f32 v11, v10, v11
	v_lshlrev_b32_e32 v32, 16, v12
	v_and_b32_e32 v33, 0xffff0000, v12
	v_lshlrev_b32_e32 v8, 16, v9
	v_and_b32_e32 v9, 0xffff0000, v9
	v_lshlrev_b32_e32 v34, 16, v35
	v_and_b32_e32 v35, 0xffff0000, v35
	v_lshlrev_b32_e32 v10, 16, v11
	v_and_b32_e32 v11, 0xffff0000, v11

.LBB0_2218:
.Lmy_ff2_g:
	global_load_dwordx4 v[52:55], v[40:41], off
	v_lshl_add_u64 v[40:41], v[40:41], 0, s[4:5]
	s_cmp_lt_u32 s2, 2
	s_cbranch_scc1 .Lmy_ff2_w1
	global_load_dwordx4 v[140:143], v[40:41], off
	v_lshl_add_u64 v[40:41], v[40:41], 0, s[4:5]
	s_cmp_lt_u32 s2, 3
	s_cbranch_scc1 .Lmy_ff2_w2
	global_load_dwordx4 v[144:147], v[40:41], off
	v_lshl_add_u64 v[40:41], v[40:41], 0, s[4:5]
	s_cmp_lt_u32 s2, 4
	s_cbranch_scc1 .Lmy_ff2_w3
	global_load_dwordx4 v[148:151], v[40:41], off
	v_lshl_add_u64 v[40:41], v[40:41], 0, s[4:5]
	s_waitcnt vmcnt(0)
	v_lshlrev_b32_e32 v44, 16, v52
	v_and_b32_e32 v45, 0xffff0000, v52
	v_lshlrev_b32_e32 v52, 16, v53
	v_and_b32_e32 v53, 0xffff0000, v53
	v_lshlrev_b32_e32 v56, 16, v54
	v_and_b32_e32 v57, 0xffff0000, v54
	v_lshlrev_b32_e32 v54, 16, v55
	v_and_b32_e32 v55, 0xffff0000, v55
	v_pk_add_f32 v[36:37], v[36:37], v[44:45]
	v_pk_add_f32 v[4:5], v[4:5], v[52:53]
	v_pk_add_f32 v[38:39], v[38:39], v[56:57]
	v_pk_add_f32 v[6:7], v[6:7], v[54:55]
	v_lshlrev_b32_e32 v44, 16, v140
	v_and_b32_e32 v45, 0xffff0000, v140
	v_lshlrev_b32_e32 v140, 16, v141
	v_and_b32_e32 v141, 0xffff0000, v141
	v_lshlrev_b32_e32 v56, 16, v142
	v_and_b32_e32 v57, 0xffff0000, v142
	v_lshlrev_b32_e32 v142, 16, v143
	v_and_b32_e32 v143, 0xffff0000, v143
	v_pk_add_f32 v[36:37], v[36:37], v[44:45]
	v_pk_add_f32 v[4:5], v[4:5], v[140:141]
	v_pk_add_f32 v[38:39], v[38:39], v[56:57]
	v_pk_add_f32 v[6:7], v[6:7], v[142:143]
	v_lshlrev_b32_e32 v44, 16, v144
	v_and_b32_e32 v45, 0xffff0000, v144
	v_lshlrev_b32_e32 v144, 16, v145
	v_and_b32_e32 v145, 0xffff0000, v145
	v_lshlrev_b32_e32 v56, 16, v146
	v_and_b32_e32 v57, 0xffff0000, v146
	v_lshlrev_b32_e32 v146, 16, v147
	v_and_b32_e32 v147, 0xffff0000, v147
	v_pk_add_f32 v[36:37], v[36:37], v[44:45]
	v_pk_add_f32 v[4:5], v[4:5], v[144:145]
	v_pk_add_f32 v[38:39], v[38:39], v[56:57]
	v_pk_add_f32 v[6:7], v[6:7], v[146:147]
	v_lshlrev_b32_e32 v44, 16, v148
	v_and_b32_e32 v45, 0xffff0000, v148
	v_lshlrev_b32_e32 v148, 16, v149
	v_and_b32_e32 v149, 0xffff0000, v149
	v_lshlrev_b32_e32 v56, 16, v150
	v_and_b32_e32 v57, 0xffff0000, v150
	v_lshlrev_b32_e32 v150, 16, v151
	v_and_b32_e32 v151, 0xffff0000, v151
	v_pk_add_f32 v[36:37], v[36:37], v[44:45]
	v_pk_add_f32 v[4:5], v[4:5], v[148:149]
	v_pk_add_f32 v[38:39], v[38:39], v[56:57]
	v_pk_add_f32 v[6:7], v[6:7], v[150:151]
	s_sub_u32 s2, s2, 4
	s_cmp_eq_u32 s2, 0
	s_cbranch_scc0 .Lmy_ff2_g
	s_branch .Lmy_ff2_d
.Lmy_ff2_w3:
	s_waitcnt vmcnt(0)
	v_lshlrev_b32_e32 v44, 16, v52
	v_and_b32_e32 v45, 0xffff0000, v52
	v_lshlrev_b32_e32 v52, 16, v53
	v_and_b32_e32 v53, 0xffff0000, v53
	v_lshlrev_b32_e32 v56, 16, v54
	v_and_b32_e32 v57, 0xffff0000, v54
	v_lshlrev_b32_e32 v54, 16, v55
	v_and_b32_e32 v55, 0xffff0000, v55
	v_pk_add_f32 v[36:37], v[36:37], v[44:45]
	v_pk_add_f32 v[4:5], v[4:5], v[52:53]
	v_pk_add_f32 v[38:39], v[38:39], v[56:57]
	v_pk_add_f32 v[6:7], v[6:7], v[54:55]
	v_lshlrev_b32_e32 v44, 16, v140
	v_and_b32_e32 v45, 0xffff0000, v140
	v_lshlrev_b32_e32 v140, 16, v141
	v_and_b32_e32 v141, 0xffff0000, v141
	v_lshlrev_b32_e32 v56, 16, v142
	v_and_b32_e32 v57, 0xffff0000, v142
	v_lshlrev_b32_e32 v142, 16, v143
	v_and_b32_e32 v143, 0xffff0000, v143
	v_pk_add_f32 v[36:37], v[36:37], v[44:45]
	v_pk_add_f32 v[4:5], v[4:5], v[140:141]
	v_pk_add_f32 v[38:39], v[38:39], v[56:57]
	v_pk_add_f32 v[6:7], v[6:7], v[142:143]
	v_lshlrev_b32_e32 v44, 16, v144
	v_and_b32_e32 v45, 0xffff0000, v144
	v_lshlrev_b32_e32 v144, 16, v145
	v_and_b32_e32 v145, 0xffff0000, v145
	v_lshlrev_b32_e32 v56, 16, v146
	v_and_b32_e32 v57, 0xffff0000, v146
	v_lshlrev_b32_e32 v146, 16, v147
	v_and_b32_e32 v147, 0xffff0000, v147
	v_pk_add_f32 v[36:37], v[36:37], v[44:45]
	v_pk_add_f32 v[4:5], v[4:5], v[144:145]
	v_pk_add_f32 v[38:39], v[38:39], v[56:57]
	v_pk_add_f32 v[6:7], v[6:7], v[146:147]
	s_branch .Lmy_ff2_d
.Lmy_ff2_w2:
	s_waitcnt vmcnt(0)
	v_lshlrev_b32_e32 v44, 16, v52
	v_and_b32_e32 v45, 0xffff0000, v52
	v_lshlrev_b32_e32 v52, 16, v53
	v_and_b32_e32 v53, 0xffff0000, v53
	v_lshlrev_b32_e32 v56, 16, v54
	v_and_b32_e32 v57, 0xffff0000, v54
	v_lshlrev_b32_e32 v54, 16, v55
	v_and_b32_e32 v55, 0xffff0000, v55
	v_pk_add_f32 v[36:37], v[36:37], v[44:45]
	v_pk_add_f32 v[4:5], v[4:5], v[52:53]
	v_pk_add_f32 v[38:39], v[38:39], v[56:57]
	v_pk_add_f32 v[6:7], v[6:7], v[54:55]
	v_lshlrev_b32_e32 v44, 16, v140
	v_and_b32_e32 v45, 0xffff0000, v140
	v_lshlrev_b32_e32 v140, 16, v141
	v_and_b32_e32 v141, 0xffff0000, v141
	v_lshlrev_b32_e32 v56, 16, v142
	v_and_b32_e32 v57, 0xffff0000, v142
	v_lshlrev_b32_e32 v142, 16, v143
	v_and_b32_e32 v143, 0xffff0000, v143
	v_pk_add_f32 v[36:37], v[36:37], v[44:45]
	v_pk_add_f32 v[4:5], v[4:5], v[140:141]
	v_pk_add_f32 v[38:39], v[38:39], v[56:57]
	v_pk_add_f32 v[6:7], v[6:7], v[142:143]
	s_branch .Lmy_ff2_d
.Lmy_ff2_w1:
	s_waitcnt vmcnt(0)
	v_lshlrev_b32_e32 v44, 16, v52
	v_and_b32_e32 v45, 0xffff0000, v52
	v_lshlrev_b32_e32 v52, 16, v53
	v_and_b32_e32 v53, 0xffff0000, v53
	v_lshlrev_b32_e32 v56, 16, v54
	v_and_b32_e32 v57, 0xffff0000, v54
	v_lshlrev_b32_e32 v54, 16, v55
	v_and_b32_e32 v55, 0xffff0000, v55
	v_pk_add_f32 v[36:37], v[36:37], v[44:45]
	v_pk_add_f32 v[4:5], v[4:5], v[52:53]
	v_pk_add_f32 v[38:39], v[38:39], v[56:57]
	v_pk_add_f32 v[6:7], v[6:7], v[54:55]
.Lmy_ff2_d:
	v_cvt_pk_bf16_f32 v12, v36, v37
	v_cvt_pk_bf16_f32 v5, v4, v5
	v_cvt_pk_bf16_f32 v39, v38, v39
	v_cvt_pk_bf16_f32 v7, v6, v7
	v_lshlrev_b32_e32 v36, 16, v12
	v_and_b32_e32 v37, 0xffff0000, v12
	v_lshlrev_b32_e32 v4, 16, v5
	v_and_b32_e32 v5, 0xffff0000, v5
	v_lshlrev_b32_e32 v38, 16, v39
	v_and_b32_e32 v39, 0xffff0000, v39
	v_lshlrev_b32_e32 v6, 16, v7
	v_and_b32_e32 v7, 0xffff0000, v7

.LBB0_2222:
.Lmy_ff3_g:
	global_load_dwordx4 v[52:55], v[44:45], off
	v_lshl_add_u64 v[44:45], v[44:45], 0, s[4:5]
	s_cmp_lt_u32 s1, 2
	s_cbranch_scc1 .Lmy_ff3_w1
	global_load_dwordx4 v[140:143], v[44:45], off
	v_lshl_add_u64 v[44:45], v[44:45], 0, s[4:5]
	s_cmp_lt_u32 s1, 3
	s_cbranch_scc1 .Lmy_ff3_w2
	global_load_dwordx4 v[144:147], v[44:45], off
	v_lshl_add_u64 v[44:45], v[44:45], 0, s[4:5]
	s_cmp_lt_u32 s1, 4
	s_cbranch_scc1 .Lmy_ff3_w3
	global_load_dwordx4 v[148:151], v[44:45], off
	v_lshl_add_u64 v[44:45], v[44:45], 0, s[4:5]
	s_waitcnt vmcnt(0)
	v_lshlrev_b32_e32 v56, 16, v52
	v_and_b32_e32 v57, 0xffff0000, v52
	v_lshlrev_b32_e32 v52, 16, v53
	v_and_b32_e32 v53, 0xffff0000, v53
	v_lshlrev_b32_e32 v58, 16, v54
	v_and_b32_e32 v59, 0xffff0000, v54
	v_lshlrev_b32_e32 v54, 16, v55
	v_and_b32_e32 v55, 0xffff0000, v55
	v_pk_add_f32 v[40:41], v[40:41], v[56:57]
	v_pk_add_f32 v[0:1], v[0:1], v[52:53]
	v_pk_add_f32 v[42:43], v[42:43], v[58:59]
	v_pk_add_f32 v[2:3], v[2:3], v[54:55]
	v_lshlrev_b32_e32 v56, 16, v140
	v_and_b32_e32 v57, 0xffff0000, v140
	v_lshlrev_b32_e32 v140, 16, v141
	v_and_b32_e32 v141, 0xffff0000, v141
	v_lshlrev_b32_e32 v58, 16, v142
	v_and_b32_e32 v59, 0xffff0000, v142
	v_lshlrev_b32_e32 v142, 16, v143
	v_and_b32_e32 v143, 0xffff0000, v143
	v_pk_add_f32 v[40:41], v[40:41], v[56:57]
	v_pk_add_f32 v[0:1], v[0:1], v[140:141]
	v_pk_add_f32 v[42:43], v[42:43], v[58:59]
	v_pk_add_f32 v[2:3], v[2:3], v[142:143]
	v_lshlrev_b32_e32 v56, 16, v144
	v_and_b32_e32 v57, 0xffff0000, v144
	v_lshlrev_b32_e32 v144, 16, v145
	v_and_b32_e32 v145, 0xffff0000, v145
	v_lshlrev_b32_e32 v58, 16, v146
	v_and_b32_e32 v59, 0xffff0000, v146
	v_lshlrev_b32_e32 v146, 16, v147
	v_and_b32_e32 v147, 0xffff0000, v147
	v_pk_add_f32 v[40:41], v[40:41], v[56:57]
	v_pk_add_f32 v[0:1], v[0:1], v[144:145]
	v_pk_add_f32 v[42:43], v[42:43], v[58:59]
	v_pk_add_f32 v[2:3], v[2:3], v[146:147]
	v_lshlrev_b32_e32 v56, 16, v148
	v_and_b32_e32 v57, 0xffff0000, v148
	v_lshlrev_b32_e32 v148, 16, v149
	v_and_b32_e32 v149, 0xffff0000, v149
	v_lshlrev_b32_e32 v58, 16, v150
	v_and_b32_e32 v59, 0xffff0000, v150
	v_lshlrev_b32_e32 v150, 16, v151
	v_and_b32_e32 v151, 0xffff0000, v151
	v_pk_add_f32 v[40:41], v[40:41], v[56:57]
	v_pk_add_f32 v[0:1], v[0:1], v[148:149]
	v_pk_add_f32 v[42:43], v[42:43], v[58:59]
	v_pk_add_f32 v[2:3], v[2:3], v[150:151]
	s_sub_u32 s1, s1, 4
	s_cmp_eq_u32 s1, 0
	s_cbranch_scc0 .Lmy_ff3_g
	s_branch .Lmy_ff3_d
.Lmy_ff3_w3:
	s_waitcnt vmcnt(0)
	v_lshlrev_b32_e32 v56, 16, v52
	v_and_b32_e32 v57, 0xffff0000, v52
	v_lshlrev_b32_e32 v52, 16, v53
	v_and_b32_e32 v53, 0xffff0000, v53
	v_lshlrev_b32_e32 v58, 16, v54
	v_and_b32_e32 v59, 0xffff0000, v54
	v_lshlrev_b32_e32 v54, 16, v55
	v_and_b32_e32 v55, 0xffff0000, v55
	v_pk_add_f32 v[40:41], v[40:41], v[56:57]
	v_pk_add_f32 v[0:1], v[0:1], v[52:53]
	v_pk_add_f32 v[42:43], v[42:43], v[58:59]
	v_pk_add_f32 v[2:3], v[2:3], v[54:55]
	v_lshlrev_b32_e32 v56, 16, v140
	v_and_b32_e32 v57, 0xffff0000, v140
	v_lshlrev_b32_e32 v140, 16, v141
	v_and_b32_e32 v141, 0xffff0000, v141
	v_lshlrev_b32_e32 v58, 16, v142
	v_and_b32_e32 v59, 0xffff0000, v142
	v_lshlrev_b32_e32 v142, 16, v143
	v_and_b32_e32 v143, 0xffff0000, v143
	v_pk_add_f32 v[40:41], v[40:41], v[56:57]
	v_pk_add_f32 v[0:1], v[0:1], v[140:141]
	v_pk_add_f32 v[42:43], v[42:43], v[58:59]
	v_pk_add_f32 v[2:3], v[2:3], v[142:143]
	v_lshlrev_b32_e32 v56, 16, v144
	v_and_b32_e32 v57, 0xffff0000, v144
	v_lshlrev_b32_e32 v144, 16, v145
	v_and_b32_e32 v145, 0xffff0000, v145
	v_lshlrev_b32_e32 v58, 16, v146
	v_and_b32_e32 v59, 0xffff0000, v146
	v_lshlrev_b32_e32 v146, 16, v147
	v_and_b32_e32 v147, 0xffff0000, v147
	v_pk_add_f32 v[40:41], v[40:41], v[56:57]
	v_pk_add_f32 v[0:1], v[0:1], v[144:145]
	v_pk_add_f32 v[42:43], v[42:43], v[58:59]
	v_pk_add_f32 v[2:3], v[2:3], v[146:147]
	s_branch .Lmy_ff3_d
.Lmy_ff3_w2:
	s_waitcnt vmcnt(0)
	v_lshlrev_b32_e32 v56, 16, v52
	v_and_b32_e32 v57, 0xffff0000, v52
	v_lshlrev_b32_e32 v52, 16, v53
	v_and_b32_e32 v53, 0xffff0000, v53
	v_lshlrev_b32_e32 v58, 16, v54
	v_and_b32_e32 v59, 0xffff0000, v54
	v_lshlrev_b32_e32 v54, 16, v55
	v_and_b32_e32 v55, 0xffff0000, v55
	v_pk_add_f32 v[40:41], v[40:41], v[56:57]
	v_pk_add_f32 v[0:1], v[0:1], v[52:53]
	v_pk_add_f32 v[42:43], v[42:43], v[58:59]
	v_pk_add_f32 v[2:3], v[2:3], v[54:55]
	v_lshlrev_b32_e32 v56, 16, v140
	v_and_b32_e32 v57, 0xffff0000, v140
	v_lshlrev_b32_e32 v140, 16, v141
	v_and_b32_e32 v141, 0xffff0000, v141
	v_lshlrev_b32_e32 v58, 16, v142
	v_and_b32_e32 v59, 0xffff0000, v142
	v_lshlrev_b32_e32 v142, 16, v143
	v_and_b32_e32 v143, 0xffff0000, v143
	v_pk_add_f32 v[40:41], v[40:41], v[56:57]
	v_pk_add_f32 v[0:1], v[0:1], v[140:141]
	v_pk_add_f32 v[42:43], v[42:43], v[58:59]
	v_pk_add_f32 v[2:3], v[2:3], v[142:143]
	s_branch .Lmy_ff3_d
.Lmy_ff3_w1:
	s_waitcnt vmcnt(0)
	v_lshlrev_b32_e32 v56, 16, v52
	v_and_b32_e32 v57, 0xffff0000, v52
	v_lshlrev_b32_e32 v52, 16, v53
	v_and_b32_e32 v53, 0xffff0000, v53
	v_lshlrev_b32_e32 v58, 16, v54
	v_and_b32_e32 v59, 0xffff0000, v54
	v_lshlrev_b32_e32 v54, 16, v55
	v_and_b32_e32 v55, 0xffff0000, v55
	v_pk_add_f32 v[40:41], v[40:41], v[56:57]
	v_pk_add_f32 v[0:1], v[0:1], v[52:53]
	v_pk_add_f32 v[42:43], v[42:43], v[58:59]
	v_pk_add_f32 v[2:3], v[2:3], v[54:55]
.Lmy_ff3_d:
	v_cvt_pk_bf16_f32 v12, v40, v41
	v_cvt_pk_bf16_f32 v1, v0, v1
	v_cvt_pk_bf16_f32 v43, v42, v43
	v_cvt_pk_bf16_f32 v3, v2, v3
	v_lshlrev_b32_e32 v40, 16, v12
	v_and_b32_e32 v41, 0xffff0000, v12
	v_lshlrev_b32_e32 v0, 16, v1
	v_and_b32_e32 v1, 0xffff0000, v1
	v_lshlrev_b32_e32 v42, 16, v43
	v_and_b32_e32 v43, 0xffff0000, v43
	v_lshlrev_b32_e32 v2, 16, v3
	v_and_b32_e32 v3, 0xffff0000, v3
	s_branch .LBB0_2199
